# grid barrier: tight spin (no s_sleep) on the top-level counter poll, on the shift/mask barrier tail
# speedup vs baseline: 1.0005x; 1.0005x over previous
.Lgb1_poll:
	global_load_dword v3, v1, s[2:3] sc1
	s_waitcnt vmcnt(0)
	v_readfirstlane_b32 s13, v3
	s_nop 0
	s_cmp_ge_u32 s13, s12
	s_cbranch_scc1 .Lgb1_done
	s_branch .Lgb1_poll
